# plus: XCD-aware S5b unit order (group B operand and output lines stay on one XCD) and hand-written short-conv in-projection epilogue
# speedup vs baseline: 1.0474x; 1.0071x over previous
;     __device__ __forceinline__ void init(int M, int N, int lda, int K) { nM = M / BM; nN = N / BM; nwg = nM * nN; G = gridDim.x; c = blockIdx.x; asm volatile("" : "+s"(c), "+s"(nN));     atile = (size_t)BM * lda * 2; btile = (size_t)BM * K * 2; }
;     __device__ __forceinline__ size_t a_off(const Unit& u) const { return (size_t)u.pm * atile; }
;     __device__ __forceinline__ size_t b_off(const Unit& u) const { return (size_t)u.pn * btile; }
;     __device__ __forceinline__ void init(int K) { G = gridDim.x; c = blockIdx.x; asm volatile("" : "+s"(c)); btile = (size_t)BM * K * 2; }
;     __device__ __forceinline__ size_t a_off(const Unit& u) const { return ((size_t)u.g * NROW + (size_t)u.pm * BM) * KA * 2; }
;     ...
;     const int tid = tid_, wid = __builtin_amdgcn_readfirstlane(tid >> 6), lane = tid & 63, wr = wid >> 2, wc = wid & 3, fr = lane & 15, fq = lane >> 4;
;     asm volatile("" : "+s"(K), "+s"(lda));
;     const int nt = K / BK;
;     unsigned voffA[2], voffB[2];
; #pragma unroll
;     for (int i = 0; i < 2; ++i) { int R, C; stage_rc(tid * 16 + i * 8192, R, C); voffA[i] = (unsigned)(R * lda + C) * 2u; voffB[i] = (unsigned)(R * K + C) * 2u; }
;     const size_t kstep = (size_t)(BK * 2);
;     const size_t hstepA = (size_t)HALF * lda * 2, hstepB = (size_t)HALF * K * 2;
;     const unsigned ldsw = (unsigned)wid * 1024u;
;     const int aoff = lds_byte(wr * 64 + fr, fq * 8), boff = lds_byte(wc * 32 + fr, fq * 8);
;     ...
;     Unit cur, nxt; int ui = 0;
;     if (!S.next(0, cur)) return;
;     f32x4 epar = E.prefetch(cur, wr, wc, lane);
;     f32x4 acc[2][2][4][2];
; #pragma unroll
;     for (int a = 0; a < 2; ++a)
; #pragma unroll
;         for (int b = 0; b < 2; ++b)
; #pragma unroll
;             for (int m = 0; m < 4; ++m)
; #pragma unroll
;                 for (int n = 0; n < 2; ++n) acc[a][b][m][n] = (f32x4){0.f, 0.f, 0.f, 0.f};
;     bf16x8 At[4][2], B0[2][2], B1[2][2];
;     const char* cA = (const char*)Ap + S.a_off(cur); const char* cB = (const char*)Btp + S.b_off(cur);
;     PG8_STAGE(PG8_SB(0, 0), cB, voffB); PG8_STAGE(PG8_SA(0, 0), cA, voffA); PG8_STAGE(PG8_SB(0, 1), cB + hstepB, voffB); PG8_STAGE(PG8_SA(0, 1), cA + hstepA, voffA);
;     if (wr == 1) PG8_BAR;
;     PG8_WAIT_V(4); PG8_BAR;
;     PG8_STAGE(PG8_SB(1, 0), cB + kstep, voffB); PG8_STAGE(PG8_SA(1, 0), cA + kstep, voffA); PG8_STAGE(PG8_SB(1, 1), cB + hstepB + kstep, voffB);
.LBB0_564:
	s_or_b64 exec, exec, s[0:1]
	s_add_u32 s40, s62, 0x4384000
	v_readlane_b32 s52, v252, 40
	s_addc_u32 s41, s63, 0
	v_readlane_b32 s53, v252, 41
	v_readlane_b32 s54, v252, 42
	v_readlane_b32 s55, v252, 43
	v_readlane_b32 s56, v252, 44
	v_readlane_b32 s57, v252, 45
	v_readlane_b32 s58, v252, 46
	v_readlane_b32 s59, v252, 47
	v_writelane_b32 v252, s60, 50
	s_mov_b32 s2, s12
	s_cmp_lg_u32 s34, 0x100
	s_cbranch_scc1 .Ls5b_nomap
	s_and_b32 s0, s2, 7
	s_lshl_b32 s0, s0, 5
	s_bfe_u32 s2, s2, 0x50003
	s_or_b32 s2, s2, s0
.Ls5b_nomap:
	s_waitcnt lgkmcnt(0)
	v_mov_b32_e32 v0, v232
	v_writelane_b32 v252, s61, 51
	s_barrier
	s_movk_i32 s0, 0x180
	v_readfirstlane_b32 s3, v0
	s_movk_i32 s4, 0x180
	s_cmpk_gt_i32 s2, 0x1ff
	v_writelane_b32 v252, s62, 52
	v_writelane_b32 v252, s63, 53
	s_cbranch_scc1 .LBB0_579
	v_bfe_i32 v3, v0, 27, 1
	v_lshlrev_b32_e32 v1, 4, v0
	v_lshrrev_b32_e32 v3, 22, v3
	v_add_u32_e32 v3, v1, v3
	v_and_b32_e32 v3, 0xfffffc00, v3
	v_sub_u32_e32 v3, v1, v3
	v_lshrrev_b32_e32 v4, 4, v3
	v_ashrrev_i32_e32 v2, 31, v0
	v_bitop3_b32 v3, v4, v3, 32 bitop3:0x6c
	v_lshrrev_b32_e32 v2, 26, v2
	v_ashrrev_i32_e32 v5, 31, v3
	v_add_u32_e32 v2, v0, v2
	v_lshrrev_b32_e32 v5, 26, v5
	v_ashrrev_i32_e32 v2, 6, v2
	v_add_u32_e32 v5, v3, v5
	v_lshlrev_b32_e32 v4, 3, v2
	v_ashrrev_i32_e32 v6, 6, v5
	v_and_b32_e32 v5, 0xc0, v5
	v_and_b32_e32 v4, -16, v4
	v_lshlrev_b32_e32 v2, 5, v2
	v_sub_u32_e32 v3, v3, v5
	v_mov_b32_e32 v5, 1
	v_add_u32_e32 v4, v6, v4
	v_and_b32_e32 v2, 32, v2
	v_ashrrev_i16_sdwa v3, v5, sext(v3) dst_sel:DWORD dst_unused:UNUSED_PAD src0_sel:DWORD src1_sel:BYTE_0
	v_add_u32_sdwa v2, v2, sext(v3) dst_sel:DWORD dst_unused:UNUSED_PAD src0_sel:DWORD src1_sel:WORD_0
	v_mul_lo_u32 v3, v4, s4
	v_add_lshl_u32 v210, v2, v3, 1
	v_mul_lo_u32 v3, v4, s0
	v_add_u32_e32 v1, 0x2000, v1
	v_add_lshl_u32 v211, v2, v3, 1
	v_ashrrev_i32_e32 v2, 31, v1
	v_lshrrev_b32_e32 v2, 22, v2
	v_add_u32_e32 v2, v1, v2
	v_ashrrev_i32_e32 v2, 10, v2
	v_mul_i32_i24_e32 v3, 0x400, v2
	v_sub_u32_e32 v1, v1, v3
	v_lshrrev_b32_e32 v3, 4, v1
	v_bitop3_b32 v1, v3, v1, 32 bitop3:0x6c
	v_ashrrev_i32_e32 v4, 31, v1
	v_lshrrev_b32_e32 v4, 26, v4
	v_add_u32_e32 v4, v1, v4
	s_add_u32 s12, s62, 0x3784000
	v_lshlrev_b32_e32 v3, 3, v2
	v_ashrrev_i32_e32 v6, 6, v4
	v_and_b32_e32 v4, 0xc0, v4
	s_addc_u32 s13, s63, 0
	v_and_b32_e32 v3, -16, v3
	v_lshlrev_b32_e32 v2, 5, v2
	v_sub_u32_e32 v1, v1, v4
	s_ashr_i32 s50, s2, 3
	v_add_u32_e32 v3, v6, v3
	v_and_b32_e32 v2, 32, v2
	v_ashrrev_i16_sdwa v1, v5, sext(v1) dst_sel:DWORD dst_unused:UNUSED_PAD src0_sel:DWORD src1_sel:BYTE_0
	s_ashr_i32 s5, s4, 31
	s_and_b32 s80, s2, 7
	s_ashr_i32 s51, s50, 31
	v_add_u32_sdwa v1, v2, sext(v1) dst_sel:DWORD dst_unused:UNUSED_PAD src0_sel:DWORD src1_sel:WORD_0
	v_mul_lo_u32 v2, v3, s4
	s_lshl_b64 s[6:7], s[4:5], 8
	s_lshl_b64 s[4:5], s[50:51], 11
	s_lshl_b32 s8, s80, 8
	s_or_b32 s4, s4, s8
	s_ashr_i32 s17, s3, 6
	s_ashr_i32 s1, s0, 31
	s_mulk_i32 s5, 0x300
	s_mul_hi_u32 s8, s4, 0x300
	s_ashr_i32 s16, s3, 8
	s_lshl_b64 s[18:19], s[0:1], 8
	s_lshl_b32 s14, s17, 10
	s_add_i32 s5, s8, s5
	s_mul_i32 s9, s50, 0x30000
	s_mul_hi_i32 s8, s50, 0x30000
	s_add_u32 s24, s12, s9
	s_addc_u32 s25, s13, s8
	s_add_i32 s14, s14, 0
	s_mulk_i32 s4, 0x300
	s_and_b32 s9, s25, 0xffff
	s_add_i32 s15, s14, 0x10000
	s_add_i32 s33, s14, 0x12000
	v_add_lshl_u32 v212, v1, v2, 1
	v_mul_lo_u32 v2, v3, s0
	s_mov_b32 s11, 0x20000
	s_brev_b32 s10, -2
	s_mov_b32 s8, s24
	s_mov_b32 m0, s15
	s_add_u32 s26, s96, s4
	v_add_lshl_u32 v213, v1, v2, 1
	buffer_load_dwordx4 v211, s[8:11], 0 offen lds
	s_mov_b32 m0, s33
	s_addc_u32 s27, s97, s5
	buffer_load_dwordx4 v213, s[8:11], 0 offen lds
	s_and_b32 s9, s27, 0xffff
	s_mov_b32 s8, s26
	s_mov_b32 m0, s14
	s_add_i32 s35, s14, 0x2000
	buffer_load_dwordx4 v210, s[8:11], 0 offen lds
	s_mov_b32 m0, s35
	s_mov_b32 s22, s10
	buffer_load_dwordx4 v212, s[8:11], 0 offen lds
	s_add_u32 s8, s24, s18
	s_addc_u32 s4, s25, s19
	s_and_b32 s9, s4, 0xffff
	s_add_i32 s52, s14, 0x14000
	s_add_i32 s53, s14, 0x16000
	s_mov_b32 m0, s52
	s_add_u32 s20, s26, s6
	buffer_load_dwordx4 v211, s[8:11], 0 offen lds
	s_mov_b32 m0, s53
	s_addc_u32 s5, s27, s7
	s_add_i32 s58, s14, 0x4000
	buffer_load_dwordx4 v213, s[8:11], 0 offen lds
	s_and_b32 s21, s5, 0xffff
	s_mov_b32 s23, s11
	s_mov_b32 m0, s58
	s_add_i32 s59, s14, 0x6000
	buffer_load_dwordx4 v210, s[20:23], 0 offen lds
	s_mov_b32 m0, s59
	s_movk_i32 s87, 0x300
	buffer_load_dwordx4 v212, s[20:23], 0 offen lds
	s_cmp_lg_u32 s16, 1
	s_mov_b32 s88, 0
	s_cbranch_scc1 .LBB0_567
	s_barrier

;     __device__ __forceinline__ void operator()(const Acc& acc, const Unit& u, int wr, int wc, int fr, int fq, LAS unsigned char* lds, f32x4 epar) const {
;     ...
;         LAS float* pw = (LAS float*)(lds + STAGE_BYTES + 64 + (wr * 4 + wc) * 1024);
;         *(LAS f32x4*)(pw + (fq * 16 + fr) * 4) = epar;
;         asm volatile("s_waitcnt lgkmcnt(0)" ::: "memory");
;         float w0[NV], w1[NV], w2[NV], bb[NV];
; #pragma unroll
;         for (int i = 0; i < NV; i += 4) { const f32x4 a = *(const LAS f32x4*)(pw + NV * fq + i), b = *(const LAS f32x4*)(pw + 32 + NV * fq + i), c = *(const LAS f32x4*)(pw + 64 + NV * fq + i);
;             f32x4 d = (f32x4){0.f, 0.f, 0.f, 0.f}; if (MODE == 0) d = *(const LAS f32x4*)(pw + 96 + NV * fq + i);
; #pragma unroll
;             for (int j = 0; j < 4; ++j) { w0[i + j] = a[j]; w1[i + j] = b[j]; w2[i + j] = c[j]; bb[i + j] = d[j]; } }
;         float sq[2][4];
; #pragma unroll
;         for (int ai = 0; ai < 2; ++ai)
; #pragma unroll
;             for (int m = 0; m < 4; ++m) sq[ai][m] = pw[128 + ai * 64 + m * 16 + fr];
; #pragma unroll
;         for (int ai = 0; ai < 2; ++ai) {
;             const int strip = u.pm * 4 + ai * 2 + wr;
;             float p1prev[NV], p2prev[NV];
; #pragma unroll
;             for (int i = 0; i < NV; ++i) { p1prev[i] = 0.f; p2prev[i] = 0.f; }
; #pragma unroll
;             for (int m = 0; m < 4; ++m) {
;                 const int r = u.pm * BM + ai * HALF + wr * 64 + m * 16 + fr;
;                 const float rs = __builtin_amdgcn_rsqf(sq[ai][m] * (1.0f / DM) + RMS_EPS);
;                 float X[NV], Y[NV], o[NV];
;                 if (MODE == 0) {
; #pragma unroll
;                     for (int n = 0; n < 2; ++n)
; #pragma unroll
;                         for (int j = 0; j < 4; ++j) { X[n * 4 + j] = acc[ai][0][m][n][j] * rs; Y[n * 4 + j] = acc[ai][1][m][n][j] * rs; }
;                 } else {
; #pragma unroll
;                     for (int j = 0; j < 4; ++j) { X[j] = (acc[ai][0][m][1][j] * rs) * (acc[ai][1][m][0][j] * rs); Y[j] = acc[ai][0][m][0][j] * rs; }
;                 }
; #pragma unroll
;                 for (int i = 0; i < NV; ++i) {
;                     const float a1 = dpp_rot<0x121>(X[i]), a2 = dpp_rot<0x122>(X[i]);
;                     const float q1 = fr >= 1 ? a1 : p1prev[i], q2 = fr >= 2 ? a2 : p2prev[i];
;                     p1prev[i] = a1; p2prev[i] = a2;
.LBB0_846:
	ds_write_b128 v146, v[24:27]
	s_mov_b64 s[24:25], exec
	s_waitcnt lgkmcnt(0)
	ds_read_b128 v[186:189], v147
	ds_read_b128 v[190:193], v147 offset:128
	ds_read_b128 v[194:197], v147 offset:256
	ds_read2_b32 v[198:199], v139 offset0:128 offset1:144
	ds_read2_b32 v[200:201], v139 offset0:160 offset1:176
	ds_read2_b32 v[202:203], v139 offset0:192 offset1:208
	ds_read2_b32 v[204:205], v139 offset0:224 offset1:240
	v_lshl_add_u32 v206, s70, 8, v138
	v_lshl_or_b32 v207, s72, 6, v140
	v_lshlrev_b32_e32 v206, 11, v206
	s_lshl_b32 s22, s70, 2
	s_add_i32 s22, s22, s15
	s_mul_i32 s16, s22, 6
	v_and_b32_e32 v208, 15, v138
	v_lshl_add_u32 v206, v207, 1, v206
	v_add_u32_e32 v208, s16, v208
	v_lshlrev_b32_e32 v208, 11, v208
	s_nop 0
	v_lshl_add_u32 v208, v207, 1, v208
	s_waitcnt lgkmcnt(0)
	v_fmamk_f32 v198, v198, 0x3a800000, v148
	v_fmamk_f32 v199, v199, 0x3a800000, v148
	v_fmamk_f32 v200, v200, 0x3a800000, v148
	v_fmamk_f32 v201, v201, 0x3a800000, v148
	v_fmamk_f32 v202, v202, 0x3a800000, v148
	v_fmamk_f32 v203, v203, 0x3a800000, v148
	v_fmamk_f32 v204, v204, 0x3a800000, v148
	v_fmamk_f32 v205, v205, 0x3a800000, v148
	v_rsq_f32_e32 v198, v198
	v_rsq_f32_e32 v199, v199
	v_rsq_f32_e32 v200, v200
	v_rsq_f32_e32 v201, v201
	v_rsq_f32_e32 v202, v202
	v_rsq_f32_e32 v203, v203
	v_rsq_f32_e32 v204, v204
	v_rsq_f32_e32 v205, v205
	s_nop 0
	v_mul_f32_e32 v96, v96, v198
	v_mul_f32_e32 v97, v97, v198
	v_mul_f32_e32 v98, v98, v198
	v_mul_f32_e32 v99, v99, v198
	v_mul_f32_e32 v92, v92, v198
	v_mul_f32_e32 v93, v93, v198
	v_mul_f32_e32 v94, v94, v198
	v_mul_f32_e32 v95, v95, v198
	v_mul_f32_e32 v88, v88, v198
	v_mul_f32_e32 v89, v89, v198
	v_mul_f32_e32 v90, v90, v198
	v_mul_f32_e32 v91, v91, v198
	v_mul_f32_e32 v96, v96, v92
	v_mul_f32_e32 v97, v97, v93
	v_mul_f32_e32 v98, v98, v94
	v_mul_f32_e32 v99, v99, v95
	v_mul_f32_e32 v209, v96, v194
	v_mul_f32_e32 v210, v97, v195
	v_mul_f32_e32 v211, v98, v196
	v_mul_f32_e32 v212, v99, v197
	v_cvt_pk_bf16_f32 v218, v96, v97
	v_cvt_pk_bf16_f32 v219, v98, v99
	v_cvt_pk_bf16_f32 v220, v88, v89
	v_cvt_pk_bf16_f32 v221, v90, v91
	v_add_u32_e32 v216, 0x1000, v208
	v_add_u32_e32 v217, 0x2000, v208
	s_andn2_b64 exec, exec, s[8:9]
	global_store_dwordx2 v216, v[218:219], s[42:43]
	global_store_dwordx2 v217, v[220:221], s[42:43]
	s_mov_b64 exec, s[24:25]
	v_fmac_f32_dpp v209, v96, v190 row_shr:1 row_mask:0xf bank_mask:0xf
	v_fmac_f32_dpp v210, v97, v191 row_shr:1 row_mask:0xf bank_mask:0xf
	v_fmac_f32_dpp v211, v98, v192 row_shr:1 row_mask:0xf bank_mask:0xf
	v_fmac_f32_dpp v212, v99, v193 row_shr:1 row_mask:0xf bank_mask:0xf
	v_fmac_f32_dpp v209, v96, v186 row_shr:2 row_mask:0xf bank_mask:0xf
	v_fmac_f32_dpp v210, v97, v187 row_shr:2 row_mask:0xf bank_mask:0xf
	v_fmac_f32_dpp v211, v98, v188 row_shr:2 row_mask:0xf bank_mask:0xf
	v_fmac_f32_dpp v212, v99, v189 row_shr:2 row_mask:0xf bank_mask:0xf
	v_mul_f32_e32 v88, v209, v88
	v_mul_f32_e32 v89, v210, v89
	v_mul_f32_e32 v90, v211, v90
	v_mul_f32_e32 v91, v212, v91
	v_cvt_pk_bf16_f32 v214, v88, v89
	v_cvt_pk_bf16_f32 v215, v90, v91
	v_add_u32_e32 v216, 0x0, v206
	s_and_b64 exec, exec, s[8:9]
	global_store_dwordx2 v216, v[214:215], s[40:41] nt
	s_mov_b64 exec, s[24:25]
	v_mul_f32_e32 v84, v84, v199
	v_mul_f32_e32 v85, v85, v199
	v_mul_f32_e32 v86, v86, v199
	v_mul_f32_e32 v87, v87, v199
	v_mul_f32_e32 v80, v80, v199
	v_mul_f32_e32 v81, v81, v199
	v_mul_f32_e32 v82, v82, v199
	v_mul_f32_e32 v83, v83, v199
	v_mul_f32_e32 v76, v76, v199
	v_mul_f32_e32 v77, v77, v199
	v_mul_f32_e32 v78, v78, v199
	v_mul_f32_e32 v79, v79, v199
	v_mul_f32_e32 v84, v84, v80
	v_mul_f32_e32 v85, v85, v81
	v_mul_f32_e32 v86, v86, v82
	v_mul_f32_e32 v87, v87, v83
	v_mul_f32_e32 v209, v84, v194
	v_mul_f32_e32 v210, v85, v195
	v_mul_f32_e32 v211, v86, v196
	v_mul_f32_e32 v212, v87, v197
	v_fmac_f32_dpp v209, v84, v190 row_shr:1 row_mask:0xf bank_mask:0xf
	v_fmac_f32_dpp v210, v85, v191 row_shr:1 row_mask:0xf bank_mask:0xf
	v_fmac_f32_dpp v211, v86, v192 row_shr:1 row_mask:0xf bank_mask:0xf
	v_fmac_f32_dpp v212, v87, v193 row_shr:1 row_mask:0xf bank_mask:0xf
	v_fmac_f32_dpp v209, v84, v186 row_shr:2 row_mask:0xf bank_mask:0xf
	v_fmac_f32_dpp v210, v85, v187 row_shr:2 row_mask:0xf bank_mask:0xf
	v_fmac_f32_dpp v211, v86, v188 row_shr:2 row_mask:0xf bank_mask:0xf
	v_fmac_f32_dpp v212, v87, v189 row_shr:2 row_mask:0xf bank_mask:0xf
	v_fmac_f32_dpp v209, v96, v190 row_shl:15 row_mask:0xf bank_mask:0xf
	v_fmac_f32_dpp v210, v97, v191 row_shl:15 row_mask:0xf bank_mask:0xf
	v_fmac_f32_dpp v211, v98, v192 row_shl:15 row_mask:0xf bank_mask:0xf
	v_fmac_f32_dpp v212, v99, v193 row_shl:15 row_mask:0xf bank_mask:0xf
	v_fmac_f32_dpp v209, v96, v186 row_shl:14 row_mask:0xf bank_mask:0xf
	v_fmac_f32_dpp v210, v97, v187 row_shl:14 row_mask:0xf bank_mask:0xf
	v_fmac_f32_dpp v211, v98, v188 row_shl:14 row_mask:0xf bank_mask:0xf
	v_fmac_f32_dpp v212, v99, v189 row_shl:14 row_mask:0xf bank_mask:0xf
	v_mul_f32_e32 v76, v209, v76
	v_mul_f32_e32 v77, v210, v77
	v_mul_f32_e32 v78, v211, v78
	v_mul_f32_e32 v79, v212, v79
	v_cvt_pk_bf16_f32 v214, v76, v77
	v_cvt_pk_bf16_f32 v215, v78, v79
	v_add_u32_e32 v216, 0x8000, v206
	global_store_dwordx2 v216, v[214:215], s[40:41] nt
	v_mul_f32_e32 v72, v72, v200
	v_mul_f32_e32 v73, v73, v200
	v_mul_f32_e32 v74, v74, v200
	v_mul_f32_e32 v75, v75, v200
	v_mul_f32_e32 v68, v68, v200
	v_mul_f32_e32 v69, v69, v200
	v_mul_f32_e32 v70, v70, v200
	v_mul_f32_e32 v71, v71, v200
	v_mul_f32_e32 v64, v64, v200
	v_mul_f32_e32 v65, v65, v200
	v_mul_f32_e32 v66, v66, v200
	v_mul_f32_e32 v67, v67, v200
	v_mul_f32_e32 v72, v72, v68
	v_mul_f32_e32 v73, v73, v69
	v_mul_f32_e32 v74, v74, v70
	v_mul_f32_e32 v75, v75, v71
;     __device__ __forceinline__ void operator()(const Acc& acc, const Unit& u, int wr, int wc, int fr, int fq, LAS unsigned char* lds, f32x4 epar) const {
;     ...
;         for (int ai = 0; ai < 2; ++ai) {
;             const int strip = u.pm * 4 + ai * 2 + wr;
;             float p1prev[NV], p2prev[NV];
; #pragma unroll
;             for (int i = 0; i < NV; ++i) { p1prev[i] = 0.f; p2prev[i] = 0.f; }
; #pragma unroll
;             for (int m = 0; m < 4; ++m) {
;                 const int r = u.pm * BM + ai * HALF + wr * 64 + m * 16 + fr;
;                 const float rs = __builtin_amdgcn_rsqf(sq[ai][m] * (1.0f / DM) + RMS_EPS);
;                 float X[NV], Y[NV], o[NV];
;                 if (MODE == 0) {
; #pragma unroll
;                     for (int n = 0; n < 2; ++n)
; #pragma unroll
;                         for (int j = 0; j < 4; ++j) { X[n * 4 + j] = acc[ai][0][m][n][j] * rs; Y[n * 4 + j] = acc[ai][1][m][n][j] * rs; }
;                 } else {
; #pragma unroll
;                     for (int j = 0; j < 4; ++j) { X[j] = (acc[ai][0][m][1][j] * rs) * (acc[ai][1][m][0][j] * rs); Y[j] = acc[ai][0][m][0][j] * rs; }
;                 }
; #pragma unroll
;                 for (int i = 0; i < NV; ++i) {
;                     const float a1 = dpp_rot<0x121>(X[i]), a2 = dpp_rot<0x122>(X[i]);
;                     const float q1 = fr >= 1 ? a1 : p1prev[i], q2 = fr >= 2 ? a2 : p2prev[i];
;                     p1prev[i] = a1; p2prev[i] = a2;
;                     const float cv = w2[i] * X[i] + w1[i] * q1 + w0[i] * q2 + bb[i];
;                     o[i] = MODE == 0 ? silu_f(cv) * Y[i] : cv * Y[i];
;                 }
;                 if (m == 0 && fr < 2) {
;                     bf16_t* hx = halo + ((size_t)strip * 6 + 2 + fr) * C + c0; bf16_t* hy = halo + ((size_t)strip * 6 + 4 + fr) * C + c0;
;                     u32x4 px, py; px.x = cvt_pk_bf16(X[0], X[1]); px.y = cvt_pk_bf16(X[2], X[3]); px.z = cvt_pk_bf16(X[4 % NV], X[5 % NV]); px.w = cvt_pk_bf16(X[6 % NV], X[7 % NV]);
;                     py.x = cvt_pk_bf16(Y[0], Y[1]); py.y = cvt_pk_bf16(Y[2], Y[3]); py.z = cvt_pk_bf16(Y[4 % NV], Y[5 % NV]); py.w = cvt_pk_bf16(Y[6 % NV], Y[7 % NV]);
;                     if (MODE == 0) { *(u32x4*)hx = px; *(u32x4*)hy = py; } else { u32x2 a; a.x = px.x; a.y = px.y; *(u32x2*)hx = a; u32x2 b; b.x = py.x; b.y = py.y; *(u32x2*)hy = b; }
;                 } else {
	v_mul_f32_e32 v209, v72, v194
	v_mul_f32_e32 v210, v73, v195
	v_mul_f32_e32 v211, v74, v196
	v_mul_f32_e32 v212, v75, v197
	v_fmac_f32_dpp v209, v72, v190 row_shr:1 row_mask:0xf bank_mask:0xf
	v_fmac_f32_dpp v210, v73, v191 row_shr:1 row_mask:0xf bank_mask:0xf
	v_fmac_f32_dpp v211, v74, v192 row_shr:1 row_mask:0xf bank_mask:0xf
	v_fmac_f32_dpp v212, v75, v193 row_shr:1 row_mask:0xf bank_mask:0xf
	v_fmac_f32_dpp v209, v72, v186 row_shr:2 row_mask:0xf bank_mask:0xf
	v_fmac_f32_dpp v210, v73, v187 row_shr:2 row_mask:0xf bank_mask:0xf
	v_fmac_f32_dpp v211, v74, v188 row_shr:2 row_mask:0xf bank_mask:0xf
	v_fmac_f32_dpp v212, v75, v189 row_shr:2 row_mask:0xf bank_mask:0xf
	v_fmac_f32_dpp v209, v84, v190 row_shl:15 row_mask:0xf bank_mask:0xf
	v_fmac_f32_dpp v210, v85, v191 row_shl:15 row_mask:0xf bank_mask:0xf
	v_fmac_f32_dpp v211, v86, v192 row_shl:15 row_mask:0xf bank_mask:0xf
	v_fmac_f32_dpp v212, v87, v193 row_shl:15 row_mask:0xf bank_mask:0xf
	v_fmac_f32_dpp v209, v84, v186 row_shl:14 row_mask:0xf bank_mask:0xf
	v_fmac_f32_dpp v210, v85, v187 row_shl:14 row_mask:0xf bank_mask:0xf
	v_fmac_f32_dpp v211, v86, v188 row_shl:14 row_mask:0xf bank_mask:0xf
	v_fmac_f32_dpp v212, v87, v189 row_shl:14 row_mask:0xf bank_mask:0xf
	v_mul_f32_e32 v64, v209, v64
	v_mul_f32_e32 v65, v210, v65
	v_mul_f32_e32 v66, v211, v66
	v_mul_f32_e32 v67, v212, v67
	v_cvt_pk_bf16_f32 v214, v64, v65
	v_cvt_pk_bf16_f32 v215, v66, v67
	v_add_u32_e32 v216, 0x10000, v206
	global_store_dwordx2 v216, v[214:215], s[40:41] nt
	v_mul_f32_e32 v60, v60, v201
	v_mul_f32_e32 v61, v61, v201
	v_mul_f32_e32 v62, v62, v201
	v_mul_f32_e32 v63, v63, v201
	v_mul_f32_e32 v56, v56, v201
	v_mul_f32_e32 v57, v57, v201
	v_mul_f32_e32 v58, v58, v201
	v_mul_f32_e32 v59, v59, v201
	v_mul_f32_e32 v52, v52, v201
	v_mul_f32_e32 v53, v53, v201
	v_mul_f32_e32 v54, v54, v201
	v_mul_f32_e32 v55, v55, v201
	v_mul_f32_e32 v60, v60, v56
	v_mul_f32_e32 v61, v61, v57
	v_mul_f32_e32 v62, v62, v58
	v_mul_f32_e32 v63, v63, v59
	v_mul_f32_e32 v209, v60, v194
	v_mul_f32_e32 v210, v61, v195
	v_mul_f32_e32 v211, v62, v196
	v_mul_f32_e32 v212, v63, v197
	v_cvt_pk_bf16_f32 v218, v60, v61
	v_cvt_pk_bf16_f32 v219, v62, v63
	v_add_u32_e32 v217, 0xffff9000, v208
	s_and_b64 exec, exec, s[10:11]
	global_store_dwordx2 v217, v[218:219], s[42:43]
	s_mov_b64 exec, s[24:25]
	v_fmac_f32_dpp v209, v60, v190 row_shr:1 row_mask:0xf bank_mask:0xf
	v_fmac_f32_dpp v210, v61, v191 row_shr:1 row_mask:0xf bank_mask:0xf
	v_fmac_f32_dpp v211, v62, v192 row_shr:1 row_mask:0xf bank_mask:0xf
	v_fmac_f32_dpp v212, v63, v193 row_shr:1 row_mask:0xf bank_mask:0xf
	v_fmac_f32_dpp v209, v60, v186 row_shr:2 row_mask:0xf bank_mask:0xf
	v_fmac_f32_dpp v210, v61, v187 row_shr:2 row_mask:0xf bank_mask:0xf
	v_fmac_f32_dpp v211, v62, v188 row_shr:2 row_mask:0xf bank_mask:0xf
	v_fmac_f32_dpp v212, v63, v189 row_shr:2 row_mask:0xf bank_mask:0xf
	v_fmac_f32_dpp v209, v72, v190 row_shl:15 row_mask:0xf bank_mask:0xf
	v_fmac_f32_dpp v210, v73, v191 row_shl:15 row_mask:0xf bank_mask:0xf
	v_fmac_f32_dpp v211, v74, v192 row_shl:15 row_mask:0xf bank_mask:0xf
	v_fmac_f32_dpp v212, v75, v193 row_shl:15 row_mask:0xf bank_mask:0xf
	v_fmac_f32_dpp v209, v72, v186 row_shl:14 row_mask:0xf bank_mask:0xf
	v_fmac_f32_dpp v210, v73, v187 row_shl:14 row_mask:0xf bank_mask:0xf
	v_fmac_f32_dpp v211, v74, v188 row_shl:14 row_mask:0xf bank_mask:0xf
	v_fmac_f32_dpp v212, v75, v189 row_shl:14 row_mask:0xf bank_mask:0xf
	v_mul_f32_e32 v52, v209, v52
	v_mul_f32_e32 v53, v210, v53
	v_mul_f32_e32 v54, v211, v54
	v_mul_f32_e32 v55, v212, v55
	v_cvt_pk_bf16_f32 v214, v52, v53
	v_cvt_pk_bf16_f32 v215, v54, v55
	v_add_u32_e32 v216, 0x18000, v206
	global_store_dwordx2 v216, v[214:215], s[40:41] nt
	v_mul_f32_e32 v48, v48, v202
	v_mul_f32_e32 v49, v49, v202
	v_mul_f32_e32 v50, v50, v202
	v_mul_f32_e32 v51, v51, v202
	v_mul_f32_e32 v40, v40, v202
	v_mul_f32_e32 v41, v41, v202
	v_mul_f32_e32 v42, v42, v202
	v_mul_f32_e32 v43, v43, v202
	v_mul_f32_e32 v44, v44, v202
	v_mul_f32_e32 v45, v45, v202
	v_mul_f32_e32 v46, v46, v202
	v_mul_f32_e32 v47, v47, v202
	v_mul_f32_e32 v48, v48, v40
	v_mul_f32_e32 v49, v49, v41
	v_mul_f32_e32 v50, v50, v42
	v_mul_f32_e32 v51, v51, v43
	v_mul_f32_e32 v209, v48, v194
	v_mul_f32_e32 v210, v49, v195
	v_mul_f32_e32 v211, v50, v196
	v_mul_f32_e32 v212, v51, v197
	v_cvt_pk_bf16_f32 v218, v48, v49
	v_cvt_pk_bf16_f32 v219, v50, v51
	v_cvt_pk_bf16_f32 v220, v44, v45
	v_cvt_pk_bf16_f32 v221, v46, v47
	v_add_u32_e32 v216, 0x7000, v208
	v_add_u32_e32 v217, 0x8000, v208
	s_andn2_b64 exec, exec, s[8:9]
	global_store_dwordx2 v216, v[218:219], s[42:43]
	global_store_dwordx2 v217, v[220:221], s[42:43]
	s_mov_b64 exec, s[24:25]
	v_fmac_f32_dpp v209, v48, v190 row_shr:1 row_mask:0xf bank_mask:0xf
	v_fmac_f32_dpp v210, v49, v191 row_shr:1 row_mask:0xf bank_mask:0xf
	v_fmac_f32_dpp v211, v50, v192 row_shr:1 row_mask:0xf bank_mask:0xf
	v_fmac_f32_dpp v212, v51, v193 row_shr:1 row_mask:0xf bank_mask:0xf
	v_fmac_f32_dpp v209, v48, v186 row_shr:2 row_mask:0xf bank_mask:0xf
	v_fmac_f32_dpp v210, v49, v187 row_shr:2 row_mask:0xf bank_mask:0xf
	v_fmac_f32_dpp v211, v50, v188 row_shr:2 row_mask:0xf bank_mask:0xf
	v_fmac_f32_dpp v212, v51, v189 row_shr:2 row_mask:0xf bank_mask:0xf
	v_mul_f32_e32 v44, v209, v44
	v_mul_f32_e32 v45, v210, v45
	v_mul_f32_e32 v46, v211, v46
	v_mul_f32_e32 v47, v212, v47
	v_cvt_pk_bf16_f32 v214, v44, v45
	v_cvt_pk_bf16_f32 v215, v46, v47
	v_add_u32_e32 v216, 0x40000, v206
	s_and_b64 exec, exec, s[8:9]
	global_store_dwordx2 v216, v[214:215], s[40:41] nt
	s_mov_b64 exec, s[24:25]
	v_mul_f32_e32 v36, v36, v203
	v_mul_f32_e32 v37, v37, v203
	v_mul_f32_e32 v38, v38, v203
;     __device__ __forceinline__ void operator()(const Acc& acc, const Unit& u, int wr, int wc, int fr, int fq, LAS unsigned char* lds, f32x4 epar) const {
;     ...
;         for (int ai = 0; ai < 2; ++ai) {
;             const int strip = u.pm * 4 + ai * 2 + wr;
;             float p1prev[NV], p2prev[NV];
; #pragma unroll
;             for (int i = 0; i < NV; ++i) { p1prev[i] = 0.f; p2prev[i] = 0.f; }
; #pragma unroll
;             for (int m = 0; m < 4; ++m) {
;                 const int r = u.pm * BM + ai * HALF + wr * 64 + m * 16 + fr;
;                 const float rs = __builtin_amdgcn_rsqf(sq[ai][m] * (1.0f / DM) + RMS_EPS);
;                 float X[NV], Y[NV], o[NV];
;                 if (MODE == 0) {
; #pragma unroll
;                     for (int n = 0; n < 2; ++n)
; #pragma unroll
;                         for (int j = 0; j < 4; ++j) { X[n * 4 + j] = acc[ai][0][m][n][j] * rs; Y[n * 4 + j] = acc[ai][1][m][n][j] * rs; }
;                 } else {
; #pragma unroll
;                     for (int j = 0; j < 4; ++j) { X[j] = (acc[ai][0][m][1][j] * rs) * (acc[ai][1][m][0][j] * rs); Y[j] = acc[ai][0][m][0][j] * rs; }
;                 }
; #pragma unroll
;                 for (int i = 0; i < NV; ++i) {
;                     const float a1 = dpp_rot<0x121>(X[i]), a2 = dpp_rot<0x122>(X[i]);
;                     const float q1 = fr >= 1 ? a1 : p1prev[i], q2 = fr >= 2 ? a2 : p2prev[i];
;                     p1prev[i] = a1; p2prev[i] = a2;
;                     const float cv = w2[i] * X[i] + w1[i] * q1 + w0[i] * q2 + bb[i];
;                     o[i] = MODE == 0 ? silu_f(cv) * Y[i] : cv * Y[i];
;                 }
;                 if (m == 0 && fr < 2) {
;                     bf16_t* hx = halo + ((size_t)strip * 6 + 2 + fr) * C + c0; bf16_t* hy = halo + ((size_t)strip * 6 + 4 + fr) * C + c0;
;                     u32x4 px, py; px.x = cvt_pk_bf16(X[0], X[1]); px.y = cvt_pk_bf16(X[2], X[3]); px.z = cvt_pk_bf16(X[4 % NV], X[5 % NV]); px.w = cvt_pk_bf16(X[6 % NV], X[7 % NV]);
;                     py.x = cvt_pk_bf16(Y[0], Y[1]); py.y = cvt_pk_bf16(Y[2], Y[3]); py.z = cvt_pk_bf16(Y[4 % NV], Y[5 % NV]); py.w = cvt_pk_bf16(Y[6 % NV], Y[7 % NV]);
;                     if (MODE == 0) { *(u32x4*)hx = px; *(u32x4*)hy = py; } else { u32x2 a; a.x = px.x; a.y = px.y; *(u32x2*)hx = a; u32x2 b; b.x = py.x; b.y = py.y; *(u32x2*)hy = b; }
;                 } else {
	v_mul_f32_e32 v39, v39, v203
	v_mul_f32_e32 v32, v32, v203
	v_mul_f32_e32 v33, v33, v203
	v_mul_f32_e32 v34, v34, v203
	v_mul_f32_e32 v35, v35, v203
	v_mul_f32_e32 v28, v28, v203
	v_mul_f32_e32 v29, v29, v203
	v_mul_f32_e32 v30, v30, v203
	v_mul_f32_e32 v31, v31, v203
	v_mul_f32_e32 v36, v36, v32
	v_mul_f32_e32 v37, v37, v33
	v_mul_f32_e32 v38, v38, v34
	v_mul_f32_e32 v39, v39, v35
	v_mul_f32_e32 v209, v36, v194
	v_mul_f32_e32 v210, v37, v195
	v_mul_f32_e32 v211, v38, v196
	v_mul_f32_e32 v212, v39, v197
	v_fmac_f32_dpp v209, v36, v190 row_shr:1 row_mask:0xf bank_mask:0xf
	v_fmac_f32_dpp v210, v37, v191 row_shr:1 row_mask:0xf bank_mask:0xf
	v_fmac_f32_dpp v211, v38, v192 row_shr:1 row_mask:0xf bank_mask:0xf
	v_fmac_f32_dpp v212, v39, v193 row_shr:1 row_mask:0xf bank_mask:0xf
	v_fmac_f32_dpp v209, v36, v186 row_shr:2 row_mask:0xf bank_mask:0xf
	v_fmac_f32_dpp v210, v37, v187 row_shr:2 row_mask:0xf bank_mask:0xf
	v_fmac_f32_dpp v211, v38, v188 row_shr:2 row_mask:0xf bank_mask:0xf
	v_fmac_f32_dpp v212, v39, v189 row_shr:2 row_mask:0xf bank_mask:0xf
	v_fmac_f32_dpp v209, v48, v190 row_shl:15 row_mask:0xf bank_mask:0xf
	v_fmac_f32_dpp v210, v49, v191 row_shl:15 row_mask:0xf bank_mask:0xf
	v_fmac_f32_dpp v211, v50, v192 row_shl:15 row_mask:0xf bank_mask:0xf
	v_fmac_f32_dpp v212, v51, v193 row_shl:15 row_mask:0xf bank_mask:0xf
	v_fmac_f32_dpp v209, v48, v186 row_shl:14 row_mask:0xf bank_mask:0xf
	v_fmac_f32_dpp v210, v49, v187 row_shl:14 row_mask:0xf bank_mask:0xf
	v_fmac_f32_dpp v211, v50, v188 row_shl:14 row_mask:0xf bank_mask:0xf
	v_fmac_f32_dpp v212, v51, v189 row_shl:14 row_mask:0xf bank_mask:0xf
	v_mul_f32_e32 v28, v209, v28
	v_mul_f32_e32 v29, v210, v29
	v_mul_f32_e32 v30, v211, v30
	v_mul_f32_e32 v31, v212, v31
	v_cvt_pk_bf16_f32 v214, v28, v29
	v_cvt_pk_bf16_f32 v215, v30, v31
	v_add_u32_e32 v216, 0x48000, v206
	global_store_dwordx2 v216, v[214:215], s[40:41] nt
	v_mul_f32_e32 v20, v20, v204
	v_mul_f32_e32 v21, v21, v204
	v_mul_f32_e32 v22, v22, v204
	v_mul_f32_e32 v23, v23, v204
	v_mul_f32_e32 v16, v16, v204
	v_mul_f32_e32 v17, v17, v204
	v_mul_f32_e32 v18, v18, v204
	v_mul_f32_e32 v19, v19, v204
	v_mul_f32_e32 v12, v12, v204
	v_mul_f32_e32 v13, v13, v204
	v_mul_f32_e32 v14, v14, v204
	v_mul_f32_e32 v15, v15, v204
	v_mul_f32_e32 v20, v20, v16
	v_mul_f32_e32 v21, v21, v17
	v_mul_f32_e32 v22, v22, v18
	v_mul_f32_e32 v23, v23, v19
	v_mul_f32_e32 v209, v20, v194
	v_mul_f32_e32 v210, v21, v195
	v_mul_f32_e32 v211, v22, v196
	v_mul_f32_e32 v212, v23, v197
	v_fmac_f32_dpp v209, v20, v190 row_shr:1 row_mask:0xf bank_mask:0xf
	v_fmac_f32_dpp v210, v21, v191 row_shr:1 row_mask:0xf bank_mask:0xf
	v_fmac_f32_dpp v211, v22, v192 row_shr:1 row_mask:0xf bank_mask:0xf
	v_fmac_f32_dpp v212, v23, v193 row_shr:1 row_mask:0xf bank_mask:0xf
	v_fmac_f32_dpp v209, v20, v186 row_shr:2 row_mask:0xf bank_mask:0xf
	v_fmac_f32_dpp v210, v21, v187 row_shr:2 row_mask:0xf bank_mask:0xf
	v_fmac_f32_dpp v211, v22, v188 row_shr:2 row_mask:0xf bank_mask:0xf
	v_fmac_f32_dpp v212, v23, v189 row_shr:2 row_mask:0xf bank_mask:0xf
	v_fmac_f32_dpp v209, v36, v190 row_shl:15 row_mask:0xf bank_mask:0xf
	v_fmac_f32_dpp v210, v37, v191 row_shl:15 row_mask:0xf bank_mask:0xf
	v_fmac_f32_dpp v211, v38, v192 row_shl:15 row_mask:0xf bank_mask:0xf
	v_fmac_f32_dpp v212, v39, v193 row_shl:15 row_mask:0xf bank_mask:0xf
	v_fmac_f32_dpp v209, v36, v186 row_shl:14 row_mask:0xf bank_mask:0xf
	v_fmac_f32_dpp v210, v37, v187 row_shl:14 row_mask:0xf bank_mask:0xf
	v_fmac_f32_dpp v211, v38, v188 row_shl:14 row_mask:0xf bank_mask:0xf
	v_fmac_f32_dpp v212, v39, v189 row_shl:14 row_mask:0xf bank_mask:0xf
	v_mul_f32_e32 v12, v209, v12
	v_mul_f32_e32 v13, v210, v13
	v_mul_f32_e32 v14, v211, v14
	v_mul_f32_e32 v15, v212, v15
	v_cvt_pk_bf16_f32 v214, v12, v13
	v_cvt_pk_bf16_f32 v215, v14, v15
	v_add_u32_e32 v216, 0x50000, v206
	global_store_dwordx2 v216, v[214:215], s[40:41] nt
	v_mul_f32_e32 v8, v8, v205
	v_mul_f32_e32 v9, v9, v205
	v_mul_f32_e32 v10, v10, v205
	v_mul_f32_e32 v11, v11, v205
	v_mul_f32_e32 v4, v4, v205
	v_mul_f32_e32 v5, v5, v205
	v_mul_f32_e32 v6, v6, v205
	v_mul_f32_e32 v7, v7, v205
	v_mul_f32_e32 v0, v0, v205
	v_mul_f32_e32 v1, v1, v205
	v_mul_f32_e32 v2, v2, v205
	v_mul_f32_e32 v3, v3, v205
	v_mul_f32_e32 v8, v8, v4
	v_mul_f32_e32 v9, v9, v5
	v_mul_f32_e32 v10, v10, v6
	v_mul_f32_e32 v11, v11, v7
	v_mul_f32_e32 v209, v8, v194
	v_mul_f32_e32 v210, v9, v195
	v_mul_f32_e32 v211, v10, v196
	v_mul_f32_e32 v212, v11, v197
	v_cvt_pk_bf16_f32 v218, v8, v9
	v_cvt_pk_bf16_f32 v219, v10, v11
	v_add_u32_e32 v217, 0xfffff000, v208
	s_and_b64 exec, exec, s[10:11]
	global_store_dwordx2 v217, v[218:219], s[42:43]
	s_mov_b64 exec, s[24:25]
	v_fmac_f32_dpp v209, v8, v190 row_shr:1 row_mask:0xf bank_mask:0xf
	v_fmac_f32_dpp v210, v9, v191 row_shr:1 row_mask:0xf bank_mask:0xf
	v_fmac_f32_dpp v211, v10, v192 row_shr:1 row_mask:0xf bank_mask:0xf
	v_fmac_f32_dpp v212, v11, v193 row_shr:1 row_mask:0xf bank_mask:0xf
	v_fmac_f32_dpp v209, v8, v186 row_shr:2 row_mask:0xf bank_mask:0xf
	v_fmac_f32_dpp v210, v9, v187 row_shr:2 row_mask:0xf bank_mask:0xf
	v_fmac_f32_dpp v211, v10, v188 row_shr:2 row_mask:0xf bank_mask:0xf
	v_fmac_f32_dpp v212, v11, v189 row_shr:2 row_mask:0xf bank_mask:0xf
	v_fmac_f32_dpp v209, v20, v190 row_shl:15 row_mask:0xf bank_mask:0xf
	v_fmac_f32_dpp v210, v21, v191 row_shl:15 row_mask:0xf bank_mask:0xf
	v_fmac_f32_dpp v211, v22, v192 row_shl:15 row_mask:0xf bank_mask:0xf
	v_fmac_f32_dpp v212, v23, v193 row_shl:15 row_mask:0xf bank_mask:0xf
	v_fmac_f32_dpp v209, v20, v186 row_shl:14 row_mask:0xf bank_mask:0xf
	v_fmac_f32_dpp v210, v21, v187 row_shl:14 row_mask:0xf bank_mask:0xf
	v_fmac_f32_dpp v211, v22, v188 row_shl:14 row_mask:0xf bank_mask:0xf
	v_fmac_f32_dpp v212, v23, v189 row_shl:14 row_mask:0xf bank_mask:0xf
	v_mul_f32_e32 v0, v209, v0
	v_mul_f32_e32 v1, v210, v1
	v_mul_f32_e32 v2, v211, v2
	v_mul_f32_e32 v3, v212, v3
	v_cvt_pk_bf16_f32 v214, v0, v1
	v_cvt_pk_bf16_f32 v215, v2, v3
	v_add_u32_e32 v216, 0x58000, v206
	global_store_dwordx2 v216, v[214:215], s[40:41] nt
